# nt hint also on the LN row loads of Z (phases 8, 11): Z is dead after the LN read
# baseline (speedup 1.0000x reference)
.LBB0_1054:
	v_ashrrev_i32_e32 v51, 31, v50
	v_lshlrev_b64 v[74:75], 12, v[50:51]
	v_cmp_gt_i32_e64 s[2:3], s20, v50
	v_lshl_add_u64 v[80:81], s[88:89], 0, v[74:75]
	v_lshlrev_b32_e32 v76, 2, v52
	s_and_saveexec_b64 s[18:19], s[2:3]
	s_xor_b64 s[18:19], exec, s[18:19]
	s_cbranch_execz .LBB0_1056
	v_mov_b32_e32 v77, v55
	v_lshl_add_u64 v[34:35], v[80:81], 0, v[76:77]
	global_load_dwordx4 v[34:37], v[34:35], off nt

.LBB0_1058:
	s_or_b64 exec, exec, s[18:19]
	s_and_saveexec_b64 s[18:19], s[2:3]
	s_xor_b64 s[18:19], exec, s[18:19]
	s_cbranch_execz .LBB0_1060
	v_mov_b32_e32 v77, v55
	v_lshl_add_u64 v[38:39], v[80:81], 0, v[76:77]
	global_load_dwordx4 v[38:41], v[38:39], off offset:1024 nt
	s_andn2_saveexec_b64 s[18:19], s[18:19]
	s_cbranch_execz .LBB0_1062
	s_branch .LBB0_1061

.LBB0_1062:
	s_or_b64 exec, exec, s[18:19]
	s_and_saveexec_b64 s[18:19], s[2:3]
	s_xor_b64 s[18:19], exec, s[18:19]
	s_cbranch_execz .LBB0_1064
	v_mov_b32_e32 v77, v55
	v_lshl_add_u64 v[42:43], v[80:81], 0, v[76:77]
	global_load_dwordx4 v[42:45], v[42:43], off offset:2048 nt
	s_andn2_saveexec_b64 s[18:19], s[18:19]
	s_cbranch_execz .LBB0_1066
	s_branch .LBB0_1065

.LBB0_1066:
	s_or_b64 exec, exec, s[18:19]
	s_and_saveexec_b64 s[18:19], s[2:3]
	s_xor_b64 s[2:3], exec, s[18:19]
	s_cbranch_execz .LBB0_1068
	v_mov_b32_e32 v77, v55
	v_lshl_add_u64 v[46:47], v[80:81], 0, v[76:77]
	global_load_dwordx4 v[46:49], v[46:47], off offset:3072 nt
	s_andn2_saveexec_b64 s[2:3], s[2:3]
	s_cbranch_execz .LBB0_1053
	s_branch .LBB0_1069

.LBB0_1367:
	v_ashrrev_i32_e32 v51, 31, v50
	v_lshlrev_b64 v[74:75], 12, v[50:51]
	v_cmp_gt_i32_e64 s[2:3], s24, v50
	v_lshl_add_u64 v[80:81], s[88:89], 0, v[74:75]
	v_lshlrev_b32_e32 v76, 2, v52
	s_and_saveexec_b64 s[22:23], s[2:3]
	s_xor_b64 s[22:23], exec, s[22:23]
	s_cbranch_execz .LBB0_1369
	v_mov_b32_e32 v77, v55
	v_lshl_add_u64 v[34:35], v[80:81], 0, v[76:77]
	global_load_dwordx4 v[34:37], v[34:35], off nt

.LBB0_1371:
	s_or_b64 exec, exec, s[22:23]
	s_and_saveexec_b64 s[22:23], s[2:3]
	s_xor_b64 s[22:23], exec, s[22:23]
	s_cbranch_execz .LBB0_1373
	v_mov_b32_e32 v77, v55
	v_lshl_add_u64 v[38:39], v[80:81], 0, v[76:77]
	global_load_dwordx4 v[38:41], v[38:39], off offset:1024 nt
	s_andn2_saveexec_b64 s[22:23], s[22:23]
	s_cbranch_execz .LBB0_1375
	s_branch .LBB0_1374

.LBB0_1375:
	s_or_b64 exec, exec, s[22:23]
	s_and_saveexec_b64 s[22:23], s[2:3]
	s_xor_b64 s[22:23], exec, s[22:23]
	s_cbranch_execz .LBB0_1377
	v_mov_b32_e32 v77, v55
	v_lshl_add_u64 v[42:43], v[80:81], 0, v[76:77]
	global_load_dwordx4 v[42:45], v[42:43], off offset:2048 nt
	s_andn2_saveexec_b64 s[22:23], s[22:23]
	s_cbranch_execz .LBB0_1379
	s_branch .LBB0_1378

.LBB0_1379:
	s_or_b64 exec, exec, s[22:23]
	s_and_saveexec_b64 s[22:23], s[2:3]
	s_xor_b64 s[2:3], exec, s[22:23]
	s_cbranch_execz .LBB0_1381
	v_mov_b32_e32 v77, v55
	v_lshl_add_u64 v[46:47], v[80:81], 0, v[76:77]
	global_load_dwordx4 v[46:49], v[46:47], off offset:3072 nt
	s_andn2_saveexec_b64 s[2:3], s[2:3]
	s_cbranch_execz .LBB0_1366
	s_branch .LBB0_1382
